# attention items: waves 4-7 run half a tile behind waves 0-3 (mid-tile barrier + one-barrier skew)
# baseline (speedup 1.0000x reference)
.LBB0_561:
	s_or_b64 exec, exec, s[8:9]
	s_mov_b64 s[8:9], 0x20000
	s_lshl_b32 s7, s14, 6
	v_lshl_add_u64 v[140:141], v[18:19], 0, s[8:9]
	s_lshl_b32 s12, s12, 16
	v_readlane_b32 s8, v254, 50
	s_add_u32 s8, s8, s12
	v_readlane_b32 s9, v254, 51
	s_addc_u32 s9, s9, 0
	s_add_u32 s8, s8, s13
	s_addc_u32 s9, s9, 0
	v_readlane_b32 s15, v254, 52
	s_add_u32 s12, s15, s12
	v_readlane_b32 s15, v254, 53
	s_addc_u32 s15, s15, 0
	s_add_u32 s12, s12, s13
	s_addc_u32 s13, s15, 0
	v_lshl_add_u64 v[18:19], v[24:25], 1, s[8:9]
	v_lshlrev_b64 v[22:23], 8, v[22:23]
	v_readlane_b32 s8, v254, 19
	v_lshl_add_u64 v[20:21], v[26:27], 1, s[12:13]
	v_lshl_add_u64 v[142:143], v[18:19], 0, v[22:23]
	v_lshlrev_b32_e32 v18, 8, v30
	v_mov_b32_e32 v19, v1
	v_mov_b32_e32 v42, v1
	v_mov_b32_e32 v43, v1
	v_mov_b32_e32 v44, v1
	v_mov_b32_e32 v45, v1
	v_readlane_b32 s9, v254, 20
	s_mov_b32 s8, 0x8000
	v_mul_u32_u24_e32 v158, 0x90, v32
	v_lshl_add_u64 v[144:145], v[20:21], 0, v[18:19]
	v_mov_b32_e32 v169, v168
	v_writelane_b32 v254, s8, 19
	v_mov_b64_e32 v[18:19], v[42:43]
	v_mov_b64_e32 v[48:49], v[44:45]
	v_mov_b64_e32 v[22:23], v[42:43]
	v_mov_b64_e32 v[38:39], v[42:43]
	v_mov_b64_e32 v[26:27], v[42:43]
	v_mov_b64_e32 v[34:35], v[42:43]
	v_mov_b64_e32 v[30:31], v[42:43]
	s_add_i32 s15, s0, 1
	s_add_i32 s16, s1, -2
	v_mov_b32_e32 v148, v1
	v_mov_b32_e32 v149, v1
	v_writelane_b32 v254, s9, 20
	s_movk_i32 s8, 0x200
	s_mov_b32 s19, 0
	v_mov_b64_e32 v[20:21], v[44:45]
	v_mov_b64_e32 v[46:47], v[42:43]
	v_mov_b64_e32 v[24:25], v[44:45]
	v_mov_b64_e32 v[40:41], v[44:45]
	v_mov_b64_e32 v[28:29], v[44:45]
	v_mov_b64_e32 v[36:37], v[44:45]
	v_mov_b64_e32 v[32:33], v[44:45]
	v_mov_b64_e32 v[146:147], v[168:169]
	s_waitcnt lgkmcnt(0)
	s_barrier
	v_readfirstlane_b32 s98, v163
	s_cmp_lt_u32 s98, 0x100
	s_cbranch_scc1 .Lstag_in0
	s_barrier

.LBB0_571:
	v_mul_f32_e32 v159, 0xbe38aa3b, v146
	v_fmamk_f32 v122, v122, 0x3e38aa3b, v159
	v_fmamk_f32 v130, v130, 0x3e38aa3b, v159
	v_fmamk_f32 v131, v131, 0x3e38aa3b, v159
	v_fmamk_f32 v132, v132, 0x3e38aa3b, v159
	v_fmamk_f32 v133, v133, 0x3e38aa3b, v159
	v_exp_f32_e32 v146, v122
	v_fmamk_f32 v122, v123, 0x3e38aa3b, v159
	v_exp_f32_e32 v130, v130
	v_exp_f32_e32 v131, v131
	v_exp_f32_e32 v132, v132
	v_exp_f32_e32 v133, v133
	v_fmamk_f32 v126, v126, 0x3e38aa3b, v159
	v_fmamk_f32 v127, v127, 0x3e38aa3b, v159
	v_fmamk_f32 v128, v128, 0x3e38aa3b, v159
	v_fmamk_f32 v129, v129, 0x3e38aa3b, v159
	v_exp_f32_e32 v147, v122
	v_fmamk_f32 v122, v124, 0x3e38aa3b, v159
	v_fmamk_f32 v118, v118, 0x3e38aa3b, v159
	v_exp_f32_e32 v126, v126
	v_exp_f32_e32 v127, v127
	v_exp_f32_e32 v128, v128
	v_exp_f32_e32 v129, v129
	v_exp_f32_e32 v160, v122
	v_fmamk_f32 v122, v125, 0x3e38aa3b, v159
	v_exp_f32_e32 v176, v118
	v_fmamk_f32 v118, v119, 0x3e38aa3b, v159
	v_exp_f32_e32 v161, v122
	v_exp_f32_e32 v177, v118
	v_fmamk_f32 v118, v120, 0x3e38aa3b, v159
	v_fmac_f32_e32 v159, 0x3e38aa3b, v121
	v_exp_f32_e32 v178, v118
	v_exp_f32_e32 v179, v159
	v_pk_add_f32 v[118:119], v[130:131], v[132:133]
	v_pk_add_f32 v[120:121], v[126:127], v[128:129]
	v_pk_add_f32 v[118:119], v[118:119], 0 op_sel_hi:[1,0]
	v_cvt_pk_bf16_f32 v122, v126, v127
	v_pk_add_f32 v[118:119], v[120:121], v[118:119]
	v_pk_add_f32 v[120:121], v[146:147], v[160:161]
	v_cvt_pk_bf16_f32 v123, v128, v129
	v_pk_add_f32 v[118:119], v[120:121], v[118:119]
	v_pk_add_f32 v[120:121], v[176:177], v[178:179]
	v_cvt_pk_bf16_f32 v124, v146, v147
	v_pk_add_f32 v[118:119], v[120:121], v[118:119]
	v_cvt_pk_bf16_f32 v120, v130, v131
	v_pk_add_f32 v[118:119], v[118:119], v[118:119] op_sel:[0,1] op_sel_hi:[1,0]
	v_cvt_pk_bf16_f32 v121, v132, v133
	v_pk_add_f32 v[118:119], v[148:149], v[118:119]
	v_cvt_pk_bf16_f32 v125, v160, v161
	s_waitcnt lgkmcnt(0)
	s_barrier
	v_mfma_f32_16x16x32_bf16 v[42:45], v[98:101], v[120:123], v[42:45]
	v_max_f32_e32 v119, v115, v115
	v_cvt_pk_bf16_f32 v126, v176, v177
	v_cvt_pk_bf16_f32 v127, v178, v179
	v_mfma_f32_16x16x32_bf16 v[46:49], v[94:97], v[120:123], v[46:49]
	v_mfma_f32_16x16x32_bf16 v[38:41], v[90:93], v[120:123], v[38:41]
	v_mfma_f32_16x16x32_bf16 v[34:37], v[86:89], v[120:123], v[34:37]
	v_max_f32_e32 v120, v114, v114
	v_max_f32_e32 v119, v120, v119
	v_max3_f32 v120, v117, v110, v111
	v_max3_f32 v121, v112, v113, v106
	v_max3_f32 v119, v119, v116, v120
	v_max3_f32 v120, v107, v108, v109
	v_max3_f32 v122, v102, v103, v104
	v_max3_f32 v119, v119, v121, v120
	v_mfma_f32_16x16x32_bf16 v[42:45], v[82:85], v[124:127], v[42:45]
	v_max3_f32 v119, v119, v122, v105
	v_sub_f32_e32 v120, v119, v151
	v_mul_f32_e32 v120, 0x3e38aa3b, v120
	v_mfma_f32_16x16x32_bf16 v[46:49], v[78:81], v[124:127], v[46:49]
	v_cmp_lt_f32_e32 vcc, s9, v120
	v_mfma_f32_16x16x32_bf16 v[38:41], v[74:77], v[124:127], v[38:41]
	s_waitcnt lgkmcnt(0)
	v_mfma_f32_16x16x32_bf16 v[34:37], v[70:73], v[124:127], v[34:37]
	s_cbranch_vccz .LBB0_573
	v_mbcnt_hi_u32_b32 v120, -1, v203
	v_and_b32_e32 v122, 64, v120
	v_xor_b32_e32 v121, 16, v120
	v_add_u32_e32 v122, 64, v122
	v_cmp_lt_i32_e32 vcc, v121, v122
	s_nop 1
	v_cndmask_b32_e32 v121, v120, v121, vcc
	v_lshlrev_b32_e32 v121, 2, v121
	ds_bpermute_b32 v121, v121, v119
	v_max_f32_e32 v119, v119, v119
	s_waitcnt lgkmcnt(0)
	v_max_f32_e32 v121, v121, v121
	v_max_f32_e32 v119, v119, v121
	v_xor_b32_e32 v121, 32, v120
	v_cmp_lt_i32_e32 vcc, v121, v122
	s_nop 1
	v_cndmask_b32_e32 v120, v120, v121, vcc
	v_lshlrev_b32_e32 v120, 2, v120
	ds_bpermute_b32 v120, v120, v119
	s_waitcnt lgkmcnt(0)
	v_max3_f32 v119, v151, v119, v120
	v_sub_f32_e32 v120, v151, v119
	v_mul_f32_e32 v120, 0x3e38aa3b, v120
	v_exp_f32_e32 v120, v120
	v_mov_b32_e32 v151, v119
	v_mul_f32_e32 v149, v149, v120
	v_pk_mul_f32 v[20:21], v[20:21], v[120:121] op_sel_hi:[1,0]
	v_pk_mul_f32 v[18:19], v[18:19], v[120:121] op_sel_hi:[1,0]
	v_pk_mul_f32 v[24:25], v[24:25], v[120:121] op_sel_hi:[1,0]
	v_pk_mul_f32 v[22:23], v[22:23], v[120:121] op_sel_hi:[1,0]
	v_pk_mul_f32 v[28:29], v[28:29], v[120:121] op_sel_hi:[1,0]
	v_pk_mul_f32 v[26:27], v[26:27], v[120:121] op_sel_hi:[1,0]
	v_pk_mul_f32 v[32:33], v[32:33], v[120:121] op_sel_hi:[1,0]
	v_pk_mul_f32 v[30:31], v[30:31], v[120:121] op_sel_hi:[1,0]

.LBB0_581:
	v_mul_f32_e32 v0, 0xbe38aa3b, v146
	v_fmamk_f32 v102, v102, 0x3e38aa3b, v0
	v_fmamk_f32 v110, v110, 0x3e38aa3b, v0
	v_fmamk_f32 v111, v111, 0x3e38aa3b, v0
	v_fmamk_f32 v112, v112, 0x3e38aa3b, v0
	v_fmamk_f32 v113, v113, 0x3e38aa3b, v0
	v_exp_f32_e32 v114, v102
	v_fmamk_f32 v102, v103, 0x3e38aa3b, v0
	v_mov_b32_e32 v119, v115
	v_exp_f32_e32 v110, v110
	v_exp_f32_e32 v111, v111
	v_exp_f32_e32 v112, v112
	v_exp_f32_e32 v113, v113
	v_fmamk_f32 v106, v106, 0x3e38aa3b, v0
	v_fmamk_f32 v107, v107, 0x3e38aa3b, v0
	v_fmamk_f32 v108, v108, 0x3e38aa3b, v0
	v_fmamk_f32 v109, v109, 0x3e38aa3b, v0
	v_exp_f32_e32 v115, v102
	v_fmamk_f32 v102, v104, 0x3e38aa3b, v0
	v_fmamk_f32 v98, v98, 0x3e38aa3b, v0
	v_exp_f32_e32 v106, v106
	v_exp_f32_e32 v107, v107
	v_exp_f32_e32 v108, v108
	v_exp_f32_e32 v109, v109
	v_exp_f32_e32 v120, v102
	v_fmamk_f32 v102, v105, 0x3e38aa3b, v0
	v_exp_f32_e32 v122, v98
	v_fmamk_f32 v98, v99, 0x3e38aa3b, v0
	v_exp_f32_e32 v121, v102
	v_exp_f32_e32 v123, v98
	v_fmamk_f32 v98, v100, 0x3e38aa3b, v0
	v_fmac_f32_e32 v0, 0x3e38aa3b, v101
	v_exp_f32_e32 v124, v98
	v_exp_f32_e32 v125, v0
	v_pk_add_f32 v[98:99], v[110:111], v[112:113]
	v_pk_add_f32 v[100:101], v[106:107], v[108:109]
	v_pk_add_f32 v[98:99], v[98:99], 0 op_sel_hi:[1,0]
	v_cvt_pk_bf16_f32 v104, v114, v115
	v_pk_add_f32 v[98:99], v[100:101], v[98:99]
	v_pk_add_f32 v[100:101], v[114:115], v[120:121]
	v_cvt_pk_bf16_f32 v105, v120, v121
	v_pk_add_f32 v[98:99], v[100:101], v[98:99]
	v_pk_add_f32 v[100:101], v[122:123], v[124:125]
	v_max_f32_e32 v0, v95, v95
	v_pk_add_f32 v[98:99], v[100:101], v[98:99]
	v_cvt_pk_bf16_f32 v100, v106, v107
	v_pk_add_f32 v[98:99], v[98:99], v[98:99] op_sel:[0,1] op_sel_hi:[1,0]
	v_cvt_pk_bf16_f32 v101, v108, v109
	v_pk_add_f32 v[102:103], v[118:119], v[98:99]
	v_cvt_pk_bf16_f32 v98, v110, v111
	v_cvt_pk_bf16_f32 v99, v112, v113
	v_cvt_pk_bf16_f32 v106, v122, v123
	v_cvt_pk_bf16_f32 v107, v124, v125
	s_waitcnt lgkmcnt(0)
	s_barrier
	v_mfma_f32_16x16x32_bf16 v[42:45], v[58:61], v[98:101], v[42:45]
	s_waitcnt lgkmcnt(1)
	v_mfma_f32_16x16x32_bf16 v[46:49], v[62:65], v[98:101], v[46:49]
	v_mfma_f32_16x16x32_bf16 v[108:111], v[66:69], v[98:101], v[38:41]
	v_mfma_f32_16x16x32_bf16 v[98:101], v[74:77], v[98:101], v[34:37]
	v_mfma_f32_16x16x32_bf16 v[38:41], v[82:85], v[104:107], v[46:49]
	v_mfma_f32_16x16x32_bf16 v[46:49], v[90:93], v[104:107], v[98:101]
	s_nop 5
	v_max_f32_e32 v98, v94, v94
	v_max_f32_e32 v0, v98, v0
	v_max3_f32 v98, v97, v70, v71
	v_max3_f32 v99, v72, v73, v54
	v_max3_f32 v0, v0, v96, v98
	v_max3_f32 v98, v55, v56, v57
	v_max3_f32 v100, v50, v51, v52
	v_max3_f32 v0, v0, v99, v98
	s_waitcnt lgkmcnt(0)
	v_mfma_f32_16x16x32_bf16 v[34:37], v[78:81], v[104:107], v[42:45]
	v_max3_f32 v0, v0, v100, v53
	v_sub_f32_e32 v98, v0, v117
	v_mul_f32_e32 v98, 0x3e38aa3b, v98
	v_mfma_f32_16x16x32_bf16 v[42:45], v[86:89], v[104:107], v[108:111]
	v_cmp_lt_f32_e32 vcc, s4, v98
	s_cbranch_vccz .LBB0_583
	v_mbcnt_hi_u32_b32 v98, -1, v203
	v_and_b32_e32 v100, 64, v98
	v_xor_b32_e32 v99, 16, v98
	v_add_u32_e32 v100, 64, v100
	v_cmp_lt_i32_e32 vcc, v99, v100
	s_nop 1
	v_cndmask_b32_e32 v99, v98, v99, vcc
	v_lshlrev_b32_e32 v99, 2, v99
	ds_bpermute_b32 v99, v99, v0
	v_max_f32_e32 v0, v0, v0
	s_waitcnt lgkmcnt(0)
	v_max_f32_e32 v99, v99, v99
	v_max_f32_e32 v0, v0, v99
	v_xor_b32_e32 v99, 32, v98
	v_cmp_lt_i32_e32 vcc, v99, v100
	s_nop 1
	v_cndmask_b32_e32 v98, v98, v99, vcc
	v_lshlrev_b32_e32 v98, 2, v98
	ds_bpermute_b32 v98, v98, v0
	s_waitcnt lgkmcnt(0)
	v_max3_f32 v100, v117, v0, v98
	v_sub_f32_e32 v0, v117, v100
	v_mul_f32_e32 v0, 0x3e38aa3b, v0
	v_exp_f32_e32 v0, v0
	v_mov_b32_e32 v117, v100
	v_mul_f32_e32 v119, v119, v0
	v_pk_mul_f32 v[20:21], v[20:21], v[0:1] op_sel_hi:[1,0]
	v_pk_mul_f32 v[18:19], v[18:19], v[0:1] op_sel_hi:[1,0]
	v_pk_mul_f32 v[24:25], v[24:25], v[0:1] op_sel_hi:[1,0]
	v_pk_mul_f32 v[22:23], v[22:23], v[0:1] op_sel_hi:[1,0]
	v_pk_mul_f32 v[28:29], v[28:29], v[0:1] op_sel_hi:[1,0]
	v_pk_mul_f32 v[26:27], v[26:27], v[0:1] op_sel_hi:[1,0]
	v_pk_mul_f32 v[32:33], v[32:33], v[0:1] op_sel_hi:[1,0]
	v_pk_mul_f32 v[30:31], v[30:31], v[0:1] op_sel_hi:[1,0]

.LBB0_610:
	s_or_b64 exec, exec, s[12:13]
	s_lshl_b32 s12, s14, 7
	v_readlane_b32 s14, v254, 19
	v_readlane_b32 s15, v254, 20
	s_mov_b32 s17, s15
	s_or_b32 s16, s3, 0x6000
	s_lshl_b64 s[14:15], s[16:17], 10
	v_readlane_b32 s3, v254, 44
	s_add_u32 s3, s3, s14
	v_readlane_b32 s13, v254, 45
	s_addc_u32 s13, s13, s15
	s_lshl_b32 s14, s12, 1
	s_add_u32 s14, s3, s14
	s_mov_b32 s3, s17
	v_writelane_b32 v254, s2, 19
	v_mov_b32_e32 v27, v1
	s_addc_u32 s15, s13, 0
	v_writelane_b32 v254, s3, 20
	s_lshl_b64 s[16:17], s[16:17], 6
	v_readlane_b32 s3, v254, 46
	v_mov_b32_e32 v36, v32
	v_lshlrev_b32_e32 v46, 11, v54
	v_lshl_add_u64 v[158:159], v[28:29], 0, v[26:27]
	s_add_u32 s16, s3, s16
	v_readlane_b32 s3, v254, 47
	v_lshl_add_u64 v[28:29], v[36:37], 1, s[14:15]
	s_addc_u32 s17, s3, s17
	v_mov_b32_e32 v33, v1
	v_mov_b32_e32 v41, v1
	v_lshl_add_u64 v[28:29], v[28:29], 0, v[34:35]
	v_lshlrev_b32_e32 v34, 1, v46
	v_mov_b32_e32 v35, v1
	v_mov_b32_e32 v44, v40
	v_lshl_add_u64 v[26:27], v[32:33], 1, s[16:17]
	v_lshl_add_u64 v[32:33], v[40:41], 1, s[16:17]
	s_movk_i32 s16, 0xff80
	v_lshl_add_u64 v[34:35], s[14:15], 0, v[34:35]
	v_lshl_add_u64 v[36:37], v[44:45], 1, s[14:15]
	v_lshl_add_u64 v[26:27], v[26:27], 0, v[30:31]
	s_mov_b32 s17, -1
	v_lshl_add_u64 v[30:31], v[32:33], 0, v[38:39]
	v_lshl_add_u64 v[34:35], v[48:49], 1, v[34:35]
	v_mul_u32_u24_e32 v187, 0xd0, v54
	v_mul_u32_u24_e32 v151, 0x90, v54
	v_lshl_add_u64 v[26:27], v[26:27], 0, s[16:17]
	v_lshl_add_u64 v[30:31], v[30:31], 0, s[16:17]
	v_lshl_add_u64 v[32:33], v[36:37], 0, v[42:43]
	v_lshl_add_u64 v[176:177], v[34:35], 0, s[92:93]
	v_mov_b32_e32 v34, 0x8000
	v_mov_b32_e32 v54, v1
	v_mov_b32_e32 v55, v1
	v_cndmask_b32_e32 v194, v216, v34, vcc
	v_cndmask_b32_e32 v179, v27, v29, vcc
	v_cndmask_b32_e32 v178, v26, v28, vcc
	v_cndmask_b32_e64 v195, v216, v34, s[8:9]
	v_cndmask_b32_e64 v181, v31, v33, s[8:9]
	v_cndmask_b32_e64 v180, v30, v32, s[8:9]
	v_mov_b32_e32 v169, v168
	v_mov_b32_e32 v56, v1
	v_mov_b32_e32 v57, v1
	v_mov_b64_e32 v[26:27], v[54:55]
	v_mov_b64_e32 v[50:51], v[54:55]
	v_mov_b64_e32 v[30:31], v[54:55]
	v_mov_b64_e32 v[46:47], v[54:55]
	v_mov_b64_e32 v[34:35], v[54:55]
	v_mov_b64_e32 v[42:43], v[54:55]
	v_mov_b64_e32 v[38:39], v[54:55]
	v_ashrrev_i32_e32 v149, 31, v148
	v_ashrrev_i32_e32 v147, 31, v146
	s_add_i32 s0, s0, 1
	s_add_i32 s1, s1, -2
	v_mov_b32_e32 v182, v1
	v_mov_b32_e32 v183, v1
	s_mov_b32 s14, 0
	v_mov_b64_e32 v[28:29], v[56:57]
	v_mov_b64_e32 v[52:53], v[56:57]
	v_mov_b64_e32 v[32:33], v[56:57]
	v_mov_b64_e32 v[48:49], v[56:57]
	v_mov_b64_e32 v[36:37], v[56:57]
	v_mov_b64_e32 v[44:45], v[56:57]
	v_mov_b64_e32 v[40:41], v[56:57]
	v_mov_b64_e32 v[160:161], v[168:169]
	s_waitcnt lgkmcnt(0)
	s_barrier
	v_readfirstlane_b32 s98, v163
	s_cmp_lt_u32 s98, 0x100
	s_cbranch_scc1 .Lstag_in1
	s_barrier

.LBB0_624:
	v_mul_f32_e32 v153, 0xbe16c740, v160
	v_fmamk_f32 v130, v130, 0x3e16c740, v153
	v_exp_f32_e32 v160, v130
	v_fmamk_f32 v130, v131, 0x3e16c740, v153
	v_exp_f32_e32 v161, v130
	v_fmamk_f32 v130, v132, 0x3e16c740, v153
	v_exp_f32_e32 v196, v130
	v_fmamk_f32 v130, v133, 0x3e16c740, v153
	v_exp_f32_e32 v197, v130
	v_fmamk_f32 v130, v134, 0x3e16c740, v153
	v_exp_f32_e32 v134, v130
	v_fmamk_f32 v130, v135, 0x3e16c740, v153
	v_exp_f32_e32 v135, v130
	v_fmamk_f32 v130, v136, 0x3e16c740, v153
	v_exp_f32_e32 v136, v130
	v_fmamk_f32 v130, v137, 0x3e16c740, v153
	v_exp_f32_e32 v137, v130
	v_fmamk_f32 v130, v138, 0x3e16c740, v153
	v_exp_f32_e32 v138, v130
	v_fmamk_f32 v130, v139, 0x3e16c740, v153
	v_exp_f32_e32 v139, v130
	v_fmamk_f32 v130, v140, 0x3e16c740, v153
	v_exp_f32_e32 v140, v130
	v_fmamk_f32 v130, v141, 0x3e16c740, v153
	v_exp_f32_e32 v141, v130
	v_fmamk_f32 v130, v142, 0x3e16c740, v153
	v_exp_f32_e32 v142, v130
	v_fmamk_f32 v130, v143, 0x3e16c740, v153
	v_exp_f32_e32 v143, v130
	v_fmamk_f32 v130, v144, 0x3e16c740, v153
	v_fmac_f32_e32 v153, 0x3e16c740, v145
	v_exp_f32_e32 v144, v130
	v_exp_f32_e32 v145, v153
	v_pk_add_f32 v[130:131], v[160:161], v[196:197]
	v_pk_add_f32 v[132:133], v[134:135], v[136:137]
	v_pk_add_f32 v[130:131], v[130:131], 0 op_sel_hi:[1,0]
	v_cvt_pk_bf16_f32 v134, v134, v135
	v_pk_add_f32 v[130:131], v[132:133], v[130:131]
	v_pk_add_f32 v[132:133], v[138:139], v[140:141]
	v_cvt_pk_bf16_f32 v135, v136, v137
	v_pk_add_f32 v[130:131], v[132:133], v[130:131]
	v_pk_add_f32 v[132:133], v[142:143], v[144:145]
	v_cvt_pk_bf16_f32 v136, v138, v139
	v_pk_add_f32 v[130:131], v[132:133], v[130:131]
	v_cvt_pk_bf16_f32 v132, v160, v161
	v_pk_add_f32 v[130:131], v[130:131], v[130:131] op_sel:[0,1] op_sel_hi:[1,0]
	v_cvt_pk_bf16_f32 v133, v196, v197
	v_pk_add_f32 v[130:131], v[182:183], v[130:131]
	v_cvt_pk_bf16_f32 v137, v140, v141
	s_waitcnt lgkmcnt(0)
	s_barrier
	v_mfma_f32_16x16x32_bf16 v[54:57], v[110:113], v[132:135], v[54:57]
	v_max_f32_e32 v131, v127, v127
	v_cvt_pk_bf16_f32 v138, v142, v143
	v_cvt_pk_bf16_f32 v139, v144, v145
	s_waitcnt lgkmcnt(6)
	v_mfma_f32_16x16x32_bf16 v[50:53], v[106:109], v[132:135], v[50:53]
	s_waitcnt lgkmcnt(5)
	v_mfma_f32_16x16x32_bf16 v[46:49], v[102:105], v[132:135], v[46:49]
	s_waitcnt lgkmcnt(4)
	v_mfma_f32_16x16x32_bf16 v[42:45], v[98:101], v[132:135], v[42:45]
	v_max_f32_e32 v132, v126, v126
	v_max_f32_e32 v131, v132, v131
	v_max3_f32 v132, v129, v122, v123
	v_max3_f32 v133, v124, v125, v118
	v_max3_f32 v131, v131, v128, v132
	v_max3_f32 v132, v119, v120, v121
	v_max3_f32 v134, v114, v115, v116
	v_max3_f32 v131, v131, v133, v132
	s_waitcnt lgkmcnt(3)
	v_mfma_f32_16x16x32_bf16 v[54:57], v[94:97], v[136:139], v[54:57]
	v_max3_f32 v131, v131, v134, v117
	v_sub_f32_e32 v132, v131, v185
	v_mul_f32_e32 v132, 0x3e16c740, v132
	s_waitcnt lgkmcnt(2)
	v_mfma_f32_16x16x32_bf16 v[50:53], v[90:93], v[136:139], v[50:53]
	v_cmp_lt_f32_e32 vcc, s8, v132
	s_waitcnt lgkmcnt(1)
	v_mfma_f32_16x16x32_bf16 v[46:49], v[86:89], v[136:139], v[46:49]
	s_waitcnt lgkmcnt(0)
	v_mfma_f32_16x16x32_bf16 v[42:45], v[82:85], v[136:139], v[42:45]
	s_cbranch_vccz .LBB0_626
	v_mbcnt_hi_u32_b32 v132, -1, v203
	v_and_b32_e32 v134, 64, v132
	v_xor_b32_e32 v133, 16, v132
	v_add_u32_e32 v134, 64, v134
	v_cmp_lt_i32_e32 vcc, v133, v134
	s_nop 1
	v_cndmask_b32_e32 v133, v132, v133, vcc
	v_lshlrev_b32_e32 v133, 2, v133
	ds_bpermute_b32 v133, v133, v131
	v_max_f32_e32 v131, v131, v131
	s_waitcnt lgkmcnt(0)
	v_max_f32_e32 v133, v133, v133
	v_max_f32_e32 v131, v131, v133
	v_xor_b32_e32 v133, 32, v132
	v_cmp_lt_i32_e32 vcc, v133, v134
	s_nop 1
	v_cndmask_b32_e32 v132, v132, v133, vcc
	v_lshlrev_b32_e32 v132, 2, v132
	ds_bpermute_b32 v132, v132, v131
	s_waitcnt lgkmcnt(0)
	v_max3_f32 v131, v185, v131, v132
	v_sub_f32_e32 v132, v185, v131
	v_mul_f32_e32 v132, 0x3e16c740, v132
	v_exp_f32_e32 v132, v132
	v_mov_b32_e32 v185, v131
	v_mul_f32_e32 v183, v183, v132
	v_pk_mul_f32 v[28:29], v[28:29], v[132:133] op_sel_hi:[1,0]
	v_pk_mul_f32 v[26:27], v[26:27], v[132:133] op_sel_hi:[1,0]
	v_pk_mul_f32 v[32:33], v[32:33], v[132:133] op_sel_hi:[1,0]
	v_pk_mul_f32 v[30:31], v[30:31], v[132:133] op_sel_hi:[1,0]
	v_pk_mul_f32 v[36:37], v[36:37], v[132:133] op_sel_hi:[1,0]
	v_pk_mul_f32 v[34:35], v[34:35], v[132:133] op_sel_hi:[1,0]
	v_pk_mul_f32 v[40:41], v[40:41], v[132:133] op_sel_hi:[1,0]
	v_pk_mul_f32 v[38:39], v[38:39], v[132:133] op_sel_hi:[1,0]

.LBB0_636:
	v_mul_f32_e32 v0, 0xbe16c740, v160
	v_fmamk_f32 v106, v106, 0x3e16c740, v0
	v_fmamk_f32 v107, v107, 0x3e16c740, v0
	v_fmamk_f32 v108, v108, 0x3e16c740, v0
	v_fmamk_f32 v109, v109, 0x3e16c740, v0
	v_exp_f32_e32 v106, v106
	v_exp_f32_e32 v107, v107
	v_exp_f32_e32 v108, v108
	v_exp_f32_e32 v109, v109
	v_fmamk_f32 v110, v110, 0x3e16c740, v0
	v_fmamk_f32 v111, v111, 0x3e16c740, v0
	v_fmamk_f32 v112, v112, 0x3e16c740, v0
	v_fmamk_f32 v113, v113, 0x3e16c740, v0
	v_exp_f32_e32 v110, v110
	v_exp_f32_e32 v111, v111
	v_exp_f32_e32 v112, v112
	v_exp_f32_e32 v113, v113
	v_fmamk_f32 v114, v114, 0x3e16c740, v0
	v_fmamk_f32 v115, v115, 0x3e16c740, v0
	v_fmamk_f32 v116, v116, 0x3e16c740, v0
	v_fmamk_f32 v117, v117, 0x3e16c740, v0
	v_exp_f32_e32 v114, v114
	v_exp_f32_e32 v115, v115
	v_exp_f32_e32 v116, v116
	v_exp_f32_e32 v117, v117
	v_mov_b32_e32 v131, v123
	v_fmamk_f32 v118, v118, 0x3e16c740, v0
	v_fmamk_f32 v119, v119, 0x3e16c740, v0
	v_fmamk_f32 v120, v120, 0x3e16c740, v0
	v_fmac_f32_e32 v0, 0x3e16c740, v121
	v_pk_add_f32 v[122:123], v[106:107], v[108:109]
	v_exp_f32_e32 v118, v118
	v_exp_f32_e32 v119, v119
	v_exp_f32_e32 v120, v120
	v_exp_f32_e32 v121, v0
	v_pk_add_f32 v[122:123], v[122:123], 0 op_sel_hi:[1,0]
	v_pk_add_f32 v[126:127], v[110:111], v[112:113]
	v_cvt_pk_bf16_f32 v106, v106, v107
	v_cvt_pk_bf16_f32 v107, v108, v109
	v_cvt_pk_bf16_f32 v108, v110, v111
	v_cvt_pk_bf16_f32 v109, v112, v113
	v_pk_add_f32 v[122:123], v[126:127], v[122:123]
	v_pk_add_f32 v[126:127], v[114:115], v[116:117]
	v_cvt_pk_bf16_f32 v110, v114, v115
	v_cvt_pk_bf16_f32 v111, v116, v117
	s_waitcnt lgkmcnt(0)
	s_barrier
	v_mfma_f32_16x16x32_bf16 v[54:57], v[74:77], v[106:109], v[54:57]
	v_cvt_pk_bf16_f32 v112, v118, v119
	v_cvt_pk_bf16_f32 v113, v120, v121
	v_max_f32_e32 v0, v71, v71
	s_waitcnt lgkmcnt(2)
	v_mfma_f32_16x16x32_bf16 v[50:53], v[78:81], v[106:109], v[50:53]
	v_add_f32_e64 v122, v126, v122
	v_add_f32_e64 v123, v127, v123
	v_pk_add_f32 v[126:127], v[118:119], v[120:121]
	v_mfma_f32_16x16x32_bf16 v[114:117], v[82:85], v[106:109], v[46:49]
	v_add_f32_e64 v122, v126, v122
	v_add_f32_e64 v123, v127, v123
	v_pk_add_f32 v[122:123], v[122:123], v[122:123] op_sel:[0,1] op_sel_hi:[1,0]
	v_mfma_f32_16x16x32_bf16 v[106:109], v[86:89], v[106:109], v[42:45]
	v_add_f32_e64 v126, v130, v122
	v_add_f32_e64 v127, v131, v123
	s_waitcnt lgkmcnt(1)
	v_mfma_f32_16x16x32_bf16 v[42:45], v[90:93], v[110:113], v[54:57]
	s_waitcnt lgkmcnt(0)
	v_mfma_f32_16x16x32_bf16 v[54:57], v[102:105], v[110:113], v[106:109]
	s_nop 2
	v_max_f32_e32 v106, v70, v70
	v_max_f32_e32 v0, v106, v0
	v_max3_f32 v106, v73, v66, v67
	v_max3_f32 v107, v68, v69, v62
	v_max3_f32 v0, v0, v72, v106
	v_max3_f32 v106, v63, v64, v65
	v_max3_f32 v108, v58, v59, v60
	v_max3_f32 v0, v0, v107, v106
	v_mfma_f32_16x16x32_bf16 v[46:49], v[94:97], v[110:113], v[50:53]
	v_max3_f32 v0, v0, v108, v61
	v_sub_f32_e32 v106, v0, v125
	v_mul_f32_e32 v106, 0x3e16c740, v106
	v_mfma_f32_16x16x32_bf16 v[50:53], v[98:101], v[110:113], v[114:117]
	v_cmp_lt_f32_e32 vcc, s0, v106
	s_cbranch_vccz .LBB0_638
	v_mbcnt_hi_u32_b32 v106, -1, v203
	v_and_b32_e32 v108, 64, v106
	v_xor_b32_e32 v107, 16, v106
	v_add_u32_e32 v108, 64, v108
	v_cmp_lt_i32_e32 vcc, v107, v108
	s_nop 1
	v_cndmask_b32_e32 v107, v106, v107, vcc
	v_lshlrev_b32_e32 v107, 2, v107
	ds_bpermute_b32 v107, v107, v0
	v_max_f32_e32 v0, v0, v0
	s_waitcnt lgkmcnt(0)
	v_max_f32_e32 v107, v107, v107
	v_max_f32_e32 v0, v0, v107
	v_xor_b32_e32 v107, 32, v106
	v_cmp_lt_i32_e32 vcc, v107, v108
	s_nop 1
	v_cndmask_b32_e32 v106, v106, v107, vcc
	v_lshlrev_b32_e32 v106, 2, v106
	ds_bpermute_b32 v106, v106, v0
	s_waitcnt lgkmcnt(0)
	v_max3_f32 v106, v125, v0, v106
	v_sub_f32_e32 v0, v125, v106
	v_mul_f32_e32 v0, 0x3e16c740, v0
	v_exp_f32_e32 v0, v0
	v_mov_b32_e32 v125, v106
	v_mul_f32_e32 v131, v131, v0
	v_pk_mul_f32 v[28:29], v[28:29], v[0:1] op_sel_hi:[1,0]
	v_pk_mul_f32 v[26:27], v[26:27], v[0:1] op_sel_hi:[1,0]
	v_pk_mul_f32 v[32:33], v[32:33], v[0:1] op_sel_hi:[1,0]
	v_pk_mul_f32 v[30:31], v[30:31], v[0:1] op_sel_hi:[1,0]
	v_pk_mul_f32 v[36:37], v[36:37], v[0:1] op_sel_hi:[1,0]
	v_pk_mul_f32 v[34:35], v[34:35], v[0:1] op_sel_hi:[1,0]
	v_pk_mul_f32 v[40:41], v[40:41], v[0:1] op_sel_hi:[1,0]
	v_pk_mul_f32 v[38:39], v[38:39], v[0:1] op_sel_hi:[1,0]

.LBB0_645:
	v_readfirstlane_b32 s98, v163
	s_cmp_lt_u32 s98, 0x100
	s_cbranch_scc0 .Lstag_out
	s_barrier
